# prompt forgetting attention: key tiles whose weights are exactly 0 in f32 are not visited (rigorous bound from |q|,|k| maxima gathered in the in-proj epilogue + cumulative log-forget at tile ends); no
# speedup vs baseline: 1.0692x; 1.0262x over previous
;     DI void operator()(const f32x4 (&acc)[2][2][4][2], const pg8::Unit& u, int wr, int wc, int fr, int fq) const {
;         const Params& p = *pp;
;         const int colt = u.pn * 256, seg = colt >> 9;
;         const bool isq = (seg == 0) || (seg == 4), isg = (seg == 3) || (seg == 7), iskv = !isq && !isg;
;         const int oi = seg == 1 ? 0 : seg == 2 ? 1 : seg == 5 ? 2 : 3;
; #pragma unroll
;         for (int ai = 0; ai < 2; ++ai)
; #pragma unroll
;             for (int m = 0; m < 4; ++m) {
;                 const int R = u.pm * 256 + ai * 128 + wr * 64 + m * 16 + fr;
;                 float* fo = nullptr;
;                 if (iskv) {
;                     if (R < ROWS_P) { const int b = R / LPAD, t = R - b * LPAD; if (t < LP) fo = p.out + O_PAK + oi * PKV_SZ + ((size_t)b * LP + t) * 512 - seg * 512; }
;                     else fo = p.out + O_SAK + oi * SKV_SZ + (size_t)(R - ROWS_P) * 512 - seg * 512;
;                 }
;                 bf16_t* uo = p.u + (size_t)R * NU;
.LBB0_141:
	s_cmp_eq_u32 s100, 15
	s_cbranch_scc0 .Lp1q_epi
	s_sub_i32 s1, s0, 8
	s_cmp_lt_u32 s1, 4
	s_cbranch_scc0 .Lnrm_skip
	s_nop 7
	s_nop 7
	v_mbcnt_lo_u32_b32 v186, -1, 0
	v_mbcnt_hi_u32_b32 v186, -1, v186
	v_xor_b32_e32 v187, 16, v186
	v_lshlrev_b32_e32 v187, 2, v187
	v_xor_b32_e32 v188, 32, v186
	v_lshlrev_b32_e32 v188, 2, v188
	v_mul_f32_e32 v190, v122, v122
	v_fmac_f32_e32 v190, v123, v123
	v_fmac_f32_e32 v190, v124, v124
	v_fmac_f32_e32 v190, v125, v125
	v_fmac_f32_e32 v190, v126, v126
	v_fmac_f32_e32 v190, v127, v127
	v_fmac_f32_e32 v190, v128, v128
	v_fmac_f32_e32 v190, v129, v129
	v_mul_f32_e32 v191, v114, v114
	v_fmac_f32_e32 v191, v115, v115
	v_fmac_f32_e32 v191, v116, v116
	v_fmac_f32_e32 v191, v117, v117
	v_fmac_f32_e32 v191, v118, v118
	v_fmac_f32_e32 v191, v119, v119
	v_fmac_f32_e32 v191, v120, v120
	v_fmac_f32_e32 v191, v121, v121
	v_mul_f32_e32 v192, v106, v106
	v_fmac_f32_e32 v192, v107, v107
	v_fmac_f32_e32 v192, v108, v108
	v_fmac_f32_e32 v192, v109, v109
	v_fmac_f32_e32 v192, v110, v110
	v_fmac_f32_e32 v192, v111, v111
	v_fmac_f32_e32 v192, v112, v112
	v_fmac_f32_e32 v192, v113, v113
	v_mul_f32_e32 v193, v98, v98
	v_fmac_f32_e32 v193, v99, v99
	v_fmac_f32_e32 v193, v100, v100
	v_fmac_f32_e32 v193, v101, v101
	v_fmac_f32_e32 v193, v102, v102
	v_fmac_f32_e32 v193, v103, v103
	v_fmac_f32_e32 v193, v104, v104
	v_fmac_f32_e32 v193, v105, v105
	v_mul_f32_e32 v194, v90, v90
	v_fmac_f32_e32 v194, v91, v91
	v_fmac_f32_e32 v194, v92, v92
	v_fmac_f32_e32 v194, v93, v93
	v_fmac_f32_e32 v194, v94, v94
	v_fmac_f32_e32 v194, v95, v95
	v_fmac_f32_e32 v194, v96, v96
	v_fmac_f32_e32 v194, v97, v97
	v_mul_f32_e32 v195, v82, v82
	v_fmac_f32_e32 v195, v83, v83
	v_fmac_f32_e32 v195, v84, v84
	v_fmac_f32_e32 v195, v85, v85
	v_fmac_f32_e32 v195, v86, v86
	v_fmac_f32_e32 v195, v87, v87
	v_fmac_f32_e32 v195, v88, v88
	v_fmac_f32_e32 v195, v89, v89
	v_mul_f32_e32 v196, v74, v74
	v_fmac_f32_e32 v196, v75, v75
	v_fmac_f32_e32 v196, v76, v76
	v_fmac_f32_e32 v196, v77, v77
	v_fmac_f32_e32 v196, v78, v78
	v_fmac_f32_e32 v196, v79, v79
	v_fmac_f32_e32 v196, v80, v80
	v_fmac_f32_e32 v196, v81, v81
	v_mul_f32_e32 v197, v66, v66
	v_fmac_f32_e32 v197, v67, v67
	v_fmac_f32_e32 v197, v68, v68
	v_fmac_f32_e32 v197, v69, v69
	v_fmac_f32_e32 v197, v70, v70
	v_fmac_f32_e32 v197, v71, v71
	v_fmac_f32_e32 v197, v72, v72
	v_fmac_f32_e32 v197, v73, v73
	v_mul_f32_e32 v198, v58, v58
	v_fmac_f32_e32 v198, v59, v59
	v_fmac_f32_e32 v198, v60, v60
	v_fmac_f32_e32 v198, v61, v61
	v_fmac_f32_e32 v198, v62, v62
	v_fmac_f32_e32 v198, v63, v63
	v_fmac_f32_e32 v198, v64, v64
	v_fmac_f32_e32 v198, v65, v65
	v_mul_f32_e32 v199, v50, v50
	v_fmac_f32_e32 v199, v51, v51
	v_fmac_f32_e32 v199, v52, v52
	v_fmac_f32_e32 v199, v53, v53
	v_fmac_f32_e32 v199, v54, v54
	v_fmac_f32_e32 v199, v55, v55
	v_fmac_f32_e32 v199, v56, v56
	v_fmac_f32_e32 v199, v57, v57
	v_mul_f32_e32 v200, v42, v42
	v_fmac_f32_e32 v200, v43, v43
	v_fmac_f32_e32 v200, v44, v44
	v_fmac_f32_e32 v200, v45, v45
	v_fmac_f32_e32 v200, v46, v46
	v_fmac_f32_e32 v200, v47, v47
	v_fmac_f32_e32 v200, v48, v48
	v_fmac_f32_e32 v200, v49, v49
	v_mul_f32_e32 v201, v34, v34
	v_fmac_f32_e32 v201, v35, v35
	v_fmac_f32_e32 v201, v36, v36
	v_fmac_f32_e32 v201, v37, v37
	v_fmac_f32_e32 v201, v38, v38
	v_fmac_f32_e32 v201, v39, v39
	v_fmac_f32_e32 v201, v40, v40
	v_fmac_f32_e32 v201, v41, v41
	v_mul_f32_e32 v202, v26, v26
	v_fmac_f32_e32 v202, v27, v27
	v_fmac_f32_e32 v202, v28, v28
	v_fmac_f32_e32 v202, v29, v29
	v_fmac_f32_e32 v202, v30, v30
	v_fmac_f32_e32 v202, v31, v31
	v_fmac_f32_e32 v202, v32, v32
	v_fmac_f32_e32 v202, v33, v33
	v_mul_f32_e32 v203, v18, v18
	v_fmac_f32_e32 v203, v19, v19
	v_fmac_f32_e32 v203, v20, v20
	v_fmac_f32_e32 v203, v21, v21
	v_fmac_f32_e32 v203, v22, v22
	v_fmac_f32_e32 v203, v23, v23
	v_fmac_f32_e32 v203, v24, v24
	v_fmac_f32_e32 v203, v25, v25
	v_mul_f32_e32 v204, v10, v10
	v_fmac_f32_e32 v204, v11, v11
	v_fmac_f32_e32 v204, v12, v12
	v_fmac_f32_e32 v204, v13, v13
	v_fmac_f32_e32 v204, v14, v14
	v_fmac_f32_e32 v204, v15, v15
	v_fmac_f32_e32 v204, v16, v16
	v_fmac_f32_e32 v204, v17, v17
	v_mul_f32_e32 v205, v2, v2
	v_fmac_f32_e32 v205, v3, v3
	v_fmac_f32_e32 v205, v4, v4
	v_fmac_f32_e32 v205, v5, v5
	v_fmac_f32_e32 v205, v6, v6
	v_fmac_f32_e32 v205, v7, v7
	v_fmac_f32_e32 v205, v8, v8
	v_fmac_f32_e32 v205, v9, v9
	s_and_b64 s[8:9], s[12:13], exec
	s_cselect_b32 s7, 64, 0
	s_lshl_b32 s1, s6, 8
	s_add_i32 s7, s7, s1
	s_add_i32 s8, s7, 0
	s_mul_hi_u32 s9, s8, 0x7e07e07f
	s_lshr_b32 s9, s9, 11
	s_mul_i32 s9, s9, 0x1040
	s_sub_i32 s9, s8, s9
	s_cmp_lt_u32 s9, 0x1010
	s_cselect_b32 s9, 1, 0
	s_cmp_ge_u32 s6, 65
	s_cselect_b32 s9, 1, s9
	s_cmp_lg_u32 s9, 0
	s_cbranch_scc1 .Lnrm_ok_0
	v_mov_b32_e32 v190, 0
	v_mov_b32_e32 v191, 0
.Lnrm_ok_0:
	s_add_i32 s8, s7, 16
	s_mul_hi_u32 s9, s8, 0x7e07e07f
	s_lshr_b32 s9, s9, 11
	s_mul_i32 s9, s9, 0x1040
	s_sub_i32 s9, s8, s9
	s_cmp_lt_u32 s9, 0x1010
	s_cselect_b32 s9, 1, 0
	s_cmp_ge_u32 s6, 65
	s_cselect_b32 s9, 1, s9
	s_cmp_lg_u32 s9, 0
	s_cbranch_scc1 .Lnrm_ok_1
	v_mov_b32_e32 v192, 0
	v_mov_b32_e32 v193, 0
;     DI void operator()(const f32x4 (&acc)[2][2][4][2], const pg8::Unit& u, int wr, int wc, int fr, int fq) const {
;         const Params& p = *pp;
;         const int colt = u.pn * 256, seg = colt >> 9;
;         const bool isq = (seg == 0) || (seg == 4), isg = (seg == 3) || (seg == 7), iskv = !isq && !isg;
;         const int oi = seg == 1 ? 0 : seg == 2 ? 1 : seg == 5 ? 2 : 3;
; #pragma unroll
;         for (int ai = 0; ai < 2; ++ai)
; #pragma unroll
;             for (int m = 0; m < 4; ++m) {
;                 const int R = u.pm * 256 + ai * 128 + wr * 64 + m * 16 + fr;
;                 float* fo = nullptr;
;                 if (iskv) {
;                     if (R < ROWS_P) { const int b = R / LPAD, t = R - b * LPAD; if (t < LP) fo = p.out + O_PAK + oi * PKV_SZ + ((size_t)b * LP + t) * 512 - seg * 512; }
;                     else fo = p.out + O_SAK + oi * SKV_SZ + (size_t)(R - ROWS_P) * 512 - seg * 512;
;                 }
;                 bf16_t* uo = p.u + (size_t)R * NU;
.Lnrm_ok_1:
	s_add_i32 s8, s7, 32
	s_mul_hi_u32 s9, s8, 0x7e07e07f
	s_lshr_b32 s9, s9, 11
	s_mul_i32 s9, s9, 0x1040
	s_sub_i32 s9, s8, s9
	s_cmp_lt_u32 s9, 0x1010
	s_cselect_b32 s9, 1, 0
	s_cmp_ge_u32 s6, 65
	s_cselect_b32 s9, 1, s9
	s_cmp_lg_u32 s9, 0
	s_cbranch_scc1 .Lnrm_ok_2
	v_mov_b32_e32 v194, 0
	v_mov_b32_e32 v195, 0
.Lnrm_ok_2:
	s_add_i32 s8, s7, 48
	s_mul_hi_u32 s9, s8, 0x7e07e07f
	s_lshr_b32 s9, s9, 11
	s_mul_i32 s9, s9, 0x1040
	s_sub_i32 s9, s8, s9
	s_cmp_lt_u32 s9, 0x1010
	s_cselect_b32 s9, 1, 0
	s_cmp_ge_u32 s6, 65
	s_cselect_b32 s9, 1, s9
	s_cmp_lg_u32 s9, 0
	s_cbranch_scc1 .Lnrm_ok_3
	v_mov_b32_e32 v196, 0
	v_mov_b32_e32 v197, 0
.Lnrm_ok_3:
	s_add_i32 s8, s7, 128
	s_mul_hi_u32 s9, s8, 0x7e07e07f
	s_lshr_b32 s9, s9, 11
	s_mul_i32 s9, s9, 0x1040
	s_sub_i32 s9, s8, s9
	s_cmp_lt_u32 s9, 0x1010
	s_cselect_b32 s9, 1, 0
	s_cmp_ge_u32 s6, 65
	s_cselect_b32 s9, 1, s9
	s_cmp_lg_u32 s9, 0
	s_cbranch_scc1 .Lnrm_ok_4
	v_mov_b32_e32 v198, 0
	v_mov_b32_e32 v199, 0
.Lnrm_ok_4:
	s_add_i32 s8, s7, 144
	s_mul_hi_u32 s9, s8, 0x7e07e07f
	s_lshr_b32 s9, s9, 11
	s_mul_i32 s9, s9, 0x1040
	s_sub_i32 s9, s8, s9
	s_cmp_lt_u32 s9, 0x1010
	s_cselect_b32 s9, 1, 0
	s_cmp_ge_u32 s6, 65
	s_cselect_b32 s9, 1, s9
	s_cmp_lg_u32 s9, 0
	s_cbranch_scc1 .Lnrm_ok_5
	v_mov_b32_e32 v200, 0
	v_mov_b32_e32 v201, 0
.Lnrm_ok_5:
	s_add_i32 s8, s7, 160
	s_mul_hi_u32 s9, s8, 0x7e07e07f
	s_lshr_b32 s9, s9, 11
	s_mul_i32 s9, s9, 0x1040
	s_sub_i32 s9, s8, s9
	s_cmp_lt_u32 s9, 0x1010
	s_cselect_b32 s9, 1, 0
	s_cmp_ge_u32 s6, 65
	s_cselect_b32 s9, 1, s9
	s_cmp_lg_u32 s9, 0
	s_cbranch_scc1 .Lnrm_ok_6
	v_mov_b32_e32 v202, 0
	v_mov_b32_e32 v203, 0
.Lnrm_ok_6:
	s_add_i32 s8, s7, 176
	s_mul_hi_u32 s9, s8, 0x7e07e07f
	s_lshr_b32 s9, s9, 11
	s_mul_i32 s9, s9, 0x1040
	s_sub_i32 s9, s8, s9
	s_cmp_lt_u32 s9, 0x1010
	s_cselect_b32 s9, 1, 0
	s_cmp_ge_u32 s6, 65
	s_cselect_b32 s9, 1, s9
	s_cmp_lg_u32 s9, 0
	s_cbranch_scc1 .Lnrm_ok_7
	v_mov_b32_e32 v204, 0
	v_mov_b32_e32 v205, 0
.Lnrm_ok_7:
	ds_bpermute_b32 v206, v187, v190
	ds_bpermute_b32 v207, v187, v191
	ds_bpermute_b32 v208, v187, v192
	ds_bpermute_b32 v209, v187, v193
	ds_bpermute_b32 v210, v187, v194
	ds_bpermute_b32 v211, v187, v195
	ds_bpermute_b32 v212, v187, v196
	ds_bpermute_b32 v213, v187, v197
	ds_bpermute_b32 v214, v187, v198
	ds_bpermute_b32 v215, v187, v199
	ds_bpermute_b32 v216, v187, v200
	ds_bpermute_b32 v217, v187, v201
	ds_bpermute_b32 v218, v187, v202
	ds_bpermute_b32 v219, v187, v203
	ds_bpermute_b32 v220, v187, v204
	ds_bpermute_b32 v221, v187, v205
	s_waitcnt lgkmcnt(0)
	v_add_f32_e32 v190, v190, v206
	v_add_f32_e32 v191, v191, v207
	v_add_f32_e32 v192, v192, v208
	v_add_f32_e32 v193, v193, v209
	v_add_f32_e32 v194, v194, v210
	v_add_f32_e32 v195, v195, v211
	v_add_f32_e32 v196, v196, v212
	v_add_f32_e32 v197, v197, v213
	v_add_f32_e32 v198, v198, v214
	v_add_f32_e32 v199, v199, v215
	v_add_f32_e32 v200, v200, v216
	v_add_f32_e32 v201, v201, v217
	v_add_f32_e32 v202, v202, v218
	v_add_f32_e32 v203, v203, v219
	v_add_f32_e32 v204, v204, v220
	v_add_f32_e32 v205, v205, v221
	ds_bpermute_b32 v206, v188, v190
	ds_bpermute_b32 v207, v188, v191
	ds_bpermute_b32 v208, v188, v192
	ds_bpermute_b32 v209, v188, v193
	ds_bpermute_b32 v210, v188, v194
	ds_bpermute_b32 v211, v188, v195
	ds_bpermute_b32 v212, v188, v196
	ds_bpermute_b32 v213, v188, v197
	ds_bpermute_b32 v214, v188, v198
	ds_bpermute_b32 v215, v188, v199
	ds_bpermute_b32 v216, v188, v200
	ds_bpermute_b32 v217, v188, v201
	ds_bpermute_b32 v218, v188, v202
	ds_bpermute_b32 v219, v188, v203
	ds_bpermute_b32 v220, v188, v204
	ds_bpermute_b32 v221, v188, v205
	s_waitcnt lgkmcnt(0)
	v_add_f32_e32 v190, v190, v206
	v_add_f32_e32 v191, v191, v207
	v_add_f32_e32 v192, v192, v208
	v_add_f32_e32 v193, v193, v209
	v_add_f32_e32 v194, v194, v210
	v_add_f32_e32 v195, v195, v211
	v_add_f32_e32 v196, v196, v212
	v_add_f32_e32 v197, v197, v213
	v_add_f32_e32 v198, v198, v214
	v_add_f32_e32 v199, v199, v215
	v_add_f32_e32 v200, v200, v216
	v_add_f32_e32 v201, v201, v217
	v_add_f32_e32 v202, v202, v218
	v_add_f32_e32 v203, v203, v219
	v_add_f32_e32 v204, v204, v220
	v_add_f32_e32 v205, v205, v221
	v_max_f32_e32 v190, v190, v191
	v_max_f32_e32 v190, v190, v192
	v_max_f32_e32 v190, v190, v193
	v_max_f32_e32 v190, v190, v194
	v_max_f32_e32 v190, v190, v195
	v_max_f32_e32 v190, v190, v196
	v_max_f32_e32 v190, v190, v197
	v_max_f32_e32 v190, v190, v198
	v_max_f32_e32 v190, v190, v199
	v_max_f32_e32 v190, v190, v200
	v_max_f32_e32 v190, v190, v201
	v_max_f32_e32 v190, v190, v202
	v_max_f32_e32 v190, v190, v203
	v_max_f32_e32 v190, v190, v204
	v_max_f32_e32 v190, v190, v205
	v_xor_b32_e32 v189, 1, v186
	v_lshlrev_b32_e32 v189, 2, v189
	ds_bpermute_b32 v206, v189, v190
	s_waitcnt lgkmcnt(0)
	v_max_f32_e32 v190, v190, v206
	v_xor_b32_e32 v189, 2, v186
	v_lshlrev_b32_e32 v189, 2, v189
	ds_bpermute_b32 v206, v189, v190
	s_waitcnt lgkmcnt(0)
	v_max_f32_e32 v190, v190, v206
	v_xor_b32_e32 v189, 4, v186
	v_lshlrev_b32_e32 v189, 2, v189
	ds_bpermute_b32 v206, v189, v190
	s_waitcnt lgkmcnt(0)
	v_max_f32_e32 v190, v190, v206
	v_xor_b32_e32 v189, 8, v186
	v_lshlrev_b32_e32 v189, 2, v189
	ds_bpermute_b32 v206, v189, v190
	s_waitcnt lgkmcnt(0)
	v_max_f32_e32 v190, v190, v206
	s_cmp_lt_u32 s0, 10
	s_cselect_b32 s1, 0, 4
	s_addk_i32 s1, 0x180
	v_mov_b32_e32 v189, s1
	s_mov_b64 vcc, exec
	s_mov_b64 exec, 1
	global_atomic_umax v189, v190, s[56:57]
	s_mov_b64 exec, vcc

; #define LDS_AS __attribute__((address_space(3)))
; __global__ void __launch_bounds__(512, 2) hymba_mega(Params p) {
;     ...
;     for (int rep = 0; rep < 1 + DUP_P2; ++rep) {
;         const int cq = rep * 64;
;         LDS_AS int* sunit = (LDS_AS int*)((LDS_AS char*)smem + SM_UNIT_OFF);
;     ...
;         const bool streamer = ((blockIdx.x >> 3) & 3) == 0;
.LBB0_400:
	s_or_b64 exec, exec, s[0:1]
	v_mov_b32_e32 v251, 0x180
	global_load_dwordx2 v[252:253], v251, s[56:57] sc0 sc1
	s_waitcnt vmcnt(0)
	v_mov_b32_e32 v249, v252
	v_mov_b32_e32 v250, v253
	s_and_b32 s0, s2, 24
	s_cmp_lg_u32 s0, 0
	s_mov_b32 s0, 0x20040
	s_cselect_b64 s[12:13], -1, 0
	v_bfe_u32 v141, v0, 20, 10
	v_bfe_u32 v143, v0, 10, 10
	s_add_i32 s63, s0, 0x100
	s_mov_b32 s0, 0x20044
	v_mbcnt_lo_u32_b32 v0, -1, 0
	s_mov_b32 s11, 0
	v_mov_b32_e32 v131, 0
	s_movk_i32 s62, 0x100
	s_movk_i32 s66, 0x21f
	s_movk_i32 s67, 0x1000
	s_movk_i32 s88, 0x1010
	s_mov_b64 s[14:15], 0x10000
	s_mov_b64 s[16:17], 0x20000
	s_mov_b64 s[20:21], 0x30000
	s_movk_i32 s89, 0x90
	s_mov_b32 s90, 0xc2400000
	s_movk_i32 s91, 0x1200
	s_mov_b64 s[22:23], 0x1000
	s_mov_b32 s92, 0x12000
	s_mov_b32 s93, 0xf149f2ca
	s_movk_i32 s94, 0x2100
	s_add_i32 s95, s0, 0x100
	s_mov_b32 s96, 0x10000
	s_mov_b64 s[24:25], 0x10900
	s_mov_b64 s[26:27], 0x10940
	s_mov_b64 s[28:29], 0x1c00
	v_mov_b32_e32 v145, 0xff800000
	v_mbcnt_hi_u32_b32 v174, -1, v0
	v_mov_b32_e32 v147, 0x100
	v_mov_b32_e32 v175, 0x42000
	s_mov_b32 s97, 0
	s_waitcnt lgkmcnt(0)
	s_barrier
	s_branch .LBB0_402

; __global__ void __launch_bounds__(512, 2) hymba_mega(Params p) {
;     ...
;         for (int ph = 0; ph < 4; ++ph) {
;             const int qi = streamer ? (ph == 0 ? 0 : ph == 1 ? 2 : ph == 2 ? 1 : 3) : (ph == 0 ? 1 : ph == 1 ? 0 : ph == 2 ? 2 : 3);
.LBB0_402:
	s_and_b64 vcc, exec, s[12:13]
	s_mov_b64 s[0:1], -1
	s_cbranch_vccz .LBB0_409
	s_cmp_eq_u32 s97, 0
	s_cselect_b32 s38, 2, 3
	s_cmp_eq_u32 s97, 1
	s_cselect_b32 s38, 1, s38
	s_cmp_eq_u32 s97, 2
	s_cselect_b32 s38, 0, s38

; template <int MODE>
; DI void prompt_unit(const Params& p, int b, int h, int qt, char* smem) {
;     ...
;     const int t0 = qt * 256, wq0 = t0 + 32 * wave;
;     const int qpos = wq0 + l31;
;     const bool wave_valid = wq0 < LP;
;     const int qcol = (MODE == 0 ? 0 : 2048) + h * 64, kcol = qcol + 512, vcol = qcol + 1024, gcol = qcol + 1536;
;     const size_t rowb = (size_t)b * LPAD;
;     bf16x8 q[4];
;     {
;         const int qr = qpos < LPAD ? qpos : LPAD - 1;
;         const bf16_t* qp = p.u + (rowb + qr) * NU + qcol + 8 * hh;
; #pragma unroll
;         for (int s = 0; s < 4; ++s) q[s] = *(const bf16x8*)(qp + 16 * s);
;     }
;     AttnState st;
; #pragma unroll
;     for (int i = 0; i < 16; ++i) { st.o0[i] = 0.f; st.o1[i] = 0.f; }
;     st.m = -1e30f; st.l = 0.f;
;     const int kt_max = (4 * qt + 3) < 64 ? (4 * qt + 3) : 64;
;     const float* cb = p.c2p + (size_t)(b * 8 + h) * LPAD;
;     float cref = 0.f;
;     if (MODE == 1) cref = cb[t0 < LP ? t0 : LP - 1];
;     u32x4 rk, rv; float rbias = 0.f;
;     const int r0 = tid >> 3, c0 = tid & 7;
;     auto pload = [&](int kt) {
;         const bf16_t* kb = p.u + (rowb + (size_t)kt * 64 + r0) * NU + c0 * 8;
;         rk = *(const u32x4*)(kb + kcol); rv = *(const u32x4*)(kb + vcol);
;         if (MODE == 1 && tid < 64) rbias = cref - cb[kt * 64 + tid];
.LBB0_513:
	s_or_b64 exec, exec, s[0:1]
	v_mov_b32_e32 v0, s63
	s_waitcnt lgkmcnt(0)
	s_barrier
	ds_read_b32 v0, v0
	s_mov_b64 s[0:1], -1
	s_waitcnt lgkmcnt(0)
	v_cmp_lt_i32_e32 vcc, s66, v0
	v_readfirstlane_b32 s4, v0
	s_cbranch_vccnz .LBB0_508
	s_ashr_i32 s1, s4, 5
	v_mov_b32_e32 v4, v138
	s_sub_i32 s1, 16, s1
	s_lshl_b32 s100, s1, 2
	s_add_i32 s100, s100, -2
	s_lshl_b32 s5, s1, 8
	v_ashrrev_i32_e32 v0, 1, v4
	v_and_b32_e32 v0, 0xffffffe0, v0
	v_and_b32_e32 v5, 31, v4
	s_waitcnt vmcnt(1)
	v_add_u32_e32 v89, s5, v0
	v_or_b32_e32 v88, v89, v5
	s_bfe_u32 s0, s4, 0x20003
	v_min_i32_e32 v0, 0x103f, v88
	s_mul_i32 s8, s0, 0x1040
	s_mov_b32 s9, s11
	v_ashrrev_i32_e32 v1, 31, v0
	s_lshl_b32 s6, s4, 6
	v_lshl_add_u64 v[0:1], v[0:1], 0, s[8:9]
	s_and_b32 s10, s6, 0x1c0
	v_lshlrev_b64 v[0:1], 13, v[0:1]
	v_lshl_add_u64 v[0:1], s[68:69], 0, v[0:1]
	s_lshl_b32 s6, s10, 1
	s_mov_b32 s7, s11
	s_lshl_b32 s0, s1, 2
	s_or_b32 s34, s10, 0xa00
	v_lshl_add_u64 v[0:1], v[0:1], 0, s[6:7]
	s_or_b32 s7, s10, 0xc00
	s_or_b32 s0, s0, 3
	s_cmp_lt_u32 s1, 16
	v_bfe_u32 v6, v4, 5, 1
	s_cselect_b32 s10, s0, 64
	s_and_b32 s0, s4, 31
	v_lshlrev_b32_e32 v130, 4, v6
	s_mulk_i32 s0, 0x4100
	v_lshl_add_u64 v[0:1], v[0:1], 0, v[130:131]
	s_add_u32 s30, s72, s0
	v_lshl_add_u64 v[2:3], v[0:1], 0, s[22:23]
	v_add_co_u32_e32 v0, vcc, s67, v0
	s_addc_u32 s31, s73, 0
	s_min_u32 s0, s5, 0x100f
	v_addc_co_u32_e32 v1, vcc, 0, v1, vcc
	global_load_dwordx4 v[64:67], v[2:3], off offset:32
	global_load_dwordx4 v[68:71], v[2:3], off offset:64
	global_load_dwordx4 v[72:75], v[0:1], off
	global_load_dwordx4 v[76:79], v[2:3], off offset:96
	s_lshl_b32 s0, s0, 2
	v_ashrrev_i32_e32 v2, 3, v4
	v_mov_b32_e32 v0, s0
	v_ashrrev_i32_e32 v3, 31, v2
	s_lshl_b64 s[0:1], s[10:11], 19
	global_load_dword v95, v0, s[30:31]
	v_lshlrev_b32_e32 v252, 6, v174
	v_add_u32_e32 v252, 63, v252
	v_min_u32_e32 v252, 0x100f, v252
	v_lshlrev_b32_e32 v252, 2, v252
	global_load_dword v251, v252, s[30:31]
	v_lshl_add_u64 v[0:1], v[2:3], 0, s[8:9]
	s_add_u32 s0, s68, s0
	v_and_b32_e32 v7, 7, v4
	v_lshlrev_b64 v[0:1], 13, v[0:1]
	s_addc_u32 s1, s69, s1
	v_lshl_add_u64 v[8:9], s[0:1], 0, v[0:1]
	v_lshlrev_b32_e32 v90, 4, v7
	v_mov_b32_e32 v91, v131
	v_lshl_add_u64 v[8:9], v[8:9], 0, v[90:91]
	s_lshl_b32 s34, s34, 1
	s_mov_b32 s35, s11
	v_lshl_add_u64 v[10:11], v[8:9], 0, s[34:35]
	s_lshl_b32 s36, s7, 1
	s_mov_b32 s37, s11
	s_barrier
	v_lshl_add_u64 v[8:9], v[8:9], 0, s[36:37]
	global_load_dwordx4 v[80:83], v[10:11], off
	global_load_dwordx4 v[84:87], v[8:9], off
	v_cmp_gt_i32_e64 s[0:1], 64, v4
	v_mov_b32_e32 v97, 0
	s_and_saveexec_b64 s[4:5], s[0:1]
	s_cbranch_execz .LBB0_516
	v_lshl_add_u32 v8, s10, 6, v4
	v_ashrrev_i32_e32 v9, 31, v8
	v_lshl_add_u64 v[8:9], v[8:9], 2, s[30:31]
	global_load_dword v3, v[8:9], off
	s_waitcnt vmcnt(0)
	v_sub_f32_e32 v97, v95, v3

; #define LDS_AS __attribute__((address_space(3)))
; #define MFMA(a, b, c) __builtin_amdgcn_mfma_f32_32x32x16_bf16((a), (b), (c), 0, 0, 0)
; DI void attn_tile64_fox(LDS_AS const char* Kl, LDS_AS const char* Vl, LDS_AS const char* biasl, const bf16x8 (&q)[4], AttnState& st, int lane) {
;     const int l31 = lane & 31, hh = lane >> 5;
;     f32x16 s0, s1;
; #pragma unroll
;     for (int g = 0; g < 4; ++g) {
;         const f32x4 b0 = *(LDS_AS const f32x4*)(biasl + (8 * g + 4 * hh) * 4);
;         const f32x4 b1 = *(LDS_AS const f32x4*)(biasl + 128 + (8 * g + 4 * hh) * 4);
;         s0[4 * g] = b0[0]; s0[4 * g + 1] = b0[1]; s0[4 * g + 2] = b0[2]; s0[4 * g + 3] = b0[3];
;         s1[4 * g] = b1[0]; s1[4 * g + 1] = b1[1]; s1[4 * g + 2] = b1[2]; s1[4 * g + 3] = b1[3];
;     }
;     bf16x8 k0[4], k1[4];
; #pragma unroll
;     for (int stp = 0; stp < 4; ++stp) {
;         k1[stp] = *(LDS_AS const bf16x8*)(Kl + 32 * 144 + l31 * 144 + (2 * stp + hh) * 16);
;         k0[stp] = *(LDS_AS const bf16x8*)(Kl + l31 * 144 + (2 * stp + hh) * 16);
;     }
; #pragma unroll
;     for (int stp = 0; stp < 4; ++stp) s1 = MFMA(k1[stp], q[stp], s1);
; #pragma unroll
;     for (int stp = 0; stp < 4; ++stp) s0 = MFMA(k0[stp], q[stp], s0);
; template <int MODE>
; DI void prompt_unit(const Params& p, int b, int h, int qt, char* smem) {
;     ...
;         if (kt > 0) pload(kt - 1);
;         if (!wdone) {
;             LDS_AS const char* sb = lb + stg * PSTG;
;             if (MODE == 1 && kt * 64 + 63 < wq0) attn_tile64_fox(sb, sb + 9216, sb + 18432, q, st, lane);
.Lfoxp_entry:
	s_cmp_eq_u32 s100, -2
	s_cbranch_scc1 .LBB0_548
	s_mul_i32 s38, s98, 0x4900
	s_addk_i32 s38, 0x100
	s_mov_b32 s39, 0x9300
	s_xor_b32 s46, s98, 1
	s_mul_i32 s46, s46, 0x4900
	s_addk_i32 s46, 0x100
	s_add_i32 s10, s100, 1
	v_mul_f32_e32 v136, v249, v250
	v_sqrt_f32_e32 v136, v136
	v_lshlrev_b32_e32 v137, 6, v174
	v_mul_f32_e32 v136, 0x3f41e5f1, v136
	v_add_u32_e32 v137, 63, v137
	v_add_f32_e32 v136, v136, v95
	v_min_u32_e32 v137, 0x100f, v137
	v_add_f32_e32 v136, 0x432a0000, v136
	v_lshlrev_b32_e32 v137, 2, v137
	v_cmp_gt_f32_e32 vcc, v251, v136
	s_not_b64 s[42:43], vcc
	s_ff1_i32_b64 s42, s[42:43]
	s_cmp_lt_i32 s42, 0
	s_cselect_b32 s42, 64, s42
	s_min_i32 s42, s42, s100
	s_and_b32 s42, s42, -2
	s_sub_i32 s10, s10, s42
	s_lshl_b32 s43, s42, 8
	s_add_u32 s30, s30, s43
	s_addc_u32 s31, s31, 0
	s_mov_b32 s43, 0
	s_lshl_b64 s[42:43], s[42:43], 19
	v_lshl_add_u64 v[92:93], v[92:93], 0, s[42:43]
	s_mov_b32 s35, 0
	s_mov_b32 s37, 0
	v_add_u32_e32 v157, v104, v101
	v_add_u32_e32 v158, v105, v103
	v_add_u32_e32 v159, v98, v90
	v_xor_b32_e32 v112, 32, v174
	v_lshlrev_b32_e32 v112, 2, v112
	v_mov_b32_e32 v108, v107
	v_mov_b32_e32 v109, 0
	v_mov_b32_e32 v110, 0
	v_mov_b32_e32 v111, 0
	s_and_b64 vcc, exec, s[4:5]
	s_cbranch_vccz .Lfoxp_loop
	v_add_u32_e32 v97, s38, v104
	v_add_u32_e32 v100, s38, v157
	ds_read_b128 v[48:51], v97 offset:18560
	ds_read_b128 v[52:55], v97 offset:18592
	ds_read_b128 v[56:59], v97 offset:18624
	ds_read_b128 v[60:63], v97 offset:18656
	ds_read_b128 v[208:211], v100 offset:4608
	ds_read_b128 v[212:215], v100 offset:4640
	ds_read_b128 v[216:219], v100 offset:4672
	ds_read_b128 v[220:223], v100 offset:4704
	ds_read_b128 v[32:35], v97 offset:18432
	ds_read_b128 v[36:39], v97 offset:18464
	ds_read_b128 v[40:43], v97 offset:18496
	ds_read_b128 v[44:47], v97 offset:18528
	ds_read_b128 v[224:227], v100 offset:0
	ds_read_b128 v[228:231], v100 offset:32
	ds_read_b128 v[232:235], v100 offset:64
	ds_read_b128 v[236:239], v100 offset:96
	s_waitcnt lgkmcnt(11)
	v_mfma_f32_32x32x16_bf16 v[48:63], v[208:211], v[72:75], v[48:63]
	s_waitcnt lgkmcnt(10)
	v_mfma_f32_32x32x16_bf16 v[48:63], v[212:215], v[64:67], v[48:63]
	s_waitcnt lgkmcnt(9)
	v_mfma_f32_32x32x16_bf16 v[48:63], v[216:219], v[68:71], v[48:63]
	s_waitcnt lgkmcnt(8)
	v_mfma_f32_32x32x16_bf16 v[48:63], v[220:223], v[76:79], v[48:63]
	s_waitcnt lgkmcnt(3)
	v_mfma_f32_32x32x16_bf16 v[32:47], v[224:227], v[72:75], v[32:47]
	s_waitcnt lgkmcnt(2)
	v_mfma_f32_32x32x16_bf16 v[32:47], v[228:231], v[64:67], v[32:47]
	s_waitcnt lgkmcnt(1)
	v_mfma_f32_32x32x16_bf16 v[32:47], v[232:235], v[68:71], v[32:47]
	s_waitcnt lgkmcnt(0)
	v_mfma_f32_32x32x16_bf16 v[32:47], v[236:239], v[76:79], v[32:47]
	s_nop 7
	s_nop 7

;     DI void operator()(const f32x4 (&acc)[2][2][4][2], const pg8::Unit& u, int wr, int wc, int fr, int fq) const {
;     ...
;                 const int R = u.pm * 256 + ai * 128 + wr * 64 + m * 16 + fr;
;                 const float* xs = nullptr; float* yd = nullptr;
;                 if (R < ROWS_P) { const int b = R / LPAD, t = R - b * LPAD; if (t >= NMETA && t < LP) { const size_t idx = ((size_t)b * SEQ + t - NMETA) * DM; xs = p.x_prompt + idx; yd = p.out + O_YP + idx; } }
;                 else { const size_t idx = (size_t)(R - ROWS_P) * DM; xs = p.x_sample + idx; yd = p.out + O_YS + idx; }
;                 float ss = 0.f;
;                 if (xs) {
; #pragma unroll
;                     for (int bj = 0; bj < 2; ++bj) {
;                         const int n = colt + bj * 128 + wc * 32 + 8 * fq;
;                         const f32x4 x0 = *(const f32x4*)(xs + n), x1 = *(const f32x4*)(xs + n + 4);
;                         const f32x4 h0 = x0 + acc[ai][bj][m][0], h1 = x1 + acc[ai][bj][m][1];
;                         *(f32x4*)(yd + n) = h0; *(f32x4*)(yd + n + 4) = h1;
;                         ss += h0[0] * h0[0] + h0[1] * h0[1] + h0[2] * h0[2] + h0[3] * h0[3] + h1[0] * h1[0] + h1[1] * h1[1] + h1[2] * h1[2] + h1[3] * h1[3];
;                     }
;                 }
;                 ss += __shfl_xor(ss, 16); ss += __shfl_xor(ss, 32);
;                 if (xs && fq == 0) atomicAdd(p.rowss + R, ss);
.LBB0_620:
	s_cmp_eq_u32 s100, 15
	s_cbranch_scc0 .Lp3q_epi
	v_lshl_add_u32 v150, s94, 8, v158
	v_lshl_or_b32 v155, s42, 8, v159
	v_and_b32_e32 v151, 15, v158
	v_lshlrev_b32_e32 v155, 2, v155
	v_lshl_or_b32 v151, v151, 12, v155
	v_lshlrev_b32_e32 v152, 2, v150
	v_mov_b32_e32 v150, v155
	v_xor_b32_e32 v153, 16, v174
	v_xor_b32_e32 v154, 32, v174
	v_lshlrev_b32_e32 v153, 2, v153
	v_lshlrev_b32_e32 v154, 2, v154
	s_and_b64 s[20:21], s[72:73], exec
	s_cselect_b32 s20, 64, 0
	s_lshl_b32 s21, s94, 8
	s_add_i32 s21, s21, s20
	s_cmp_ge_u32 s94, 65
	s_cselect_b32 s96, s78, s76
	s_cselect_b32 s97, s79, s77
	s_cselect_b32 s98, s82, s54
	s_cselect_b32 s99, s83, s55
	s_mov_b32 s19, 0
	s_add_i32 s87, s21, 0
	s_mul_hi_u32 s89, s87, 0x7e07e07f
	s_lshr_b32 s89, s89, 11
	s_mul_i32 vcc_lo, s89, 0x1040
	s_sub_i32 vcc_lo, s87, vcc_lo
	s_add_i32 vcc_lo, vcc_lo, -16
	s_lshl_b32 s89, s89, 12
	s_add_i32 s89, s89, vcc_lo
	s_cmp_lt_u32 vcc_lo, 0x1000
	s_cselect_b32 vcc_hi, 1, 0
	s_sub_i32 vcc_lo, s87, 0x4100
	s_cmp_ge_u32 s94, 65
	s_cselect_b32 s89, vcc_lo, s89
	s_cselect_b32 vcc_hi, 1, vcc_hi
	s_cmp_lg_u32 vcc_hi, 0
	s_cselect_b32 s89, s89, 0
	s_lshl_b32 s20, s89, 12
	s_lshl_b32 vcc_hi, vcc_hi, 0
	s_or_b32 s19, s19, vcc_hi
	s_add_u32 s22, s96, s20
	s_addc_u32 s23, s97, 0
	global_load_dwordx4 v[176:179], v151, s[22:23]
	global_load_dwordx4 v[180:183], v151, s[22:23] offset:16
	global_load_dwordx4 v[184:187], v151, s[22:23] offset:512
	global_load_dwordx4 v[188:191], v151, s[22:23] offset:528
	s_add_i32 s87, s21, 16
	s_mul_hi_u32 s89, s87, 0x7e07e07f
	s_lshr_b32 s89, s89, 11
	s_mul_i32 vcc_lo, s89, 0x1040
	s_sub_i32 vcc_lo, s87, vcc_lo
	s_add_i32 vcc_lo, vcc_lo, -16
	s_lshl_b32 s89, s89, 12
	s_add_i32 s89, s89, vcc_lo
	s_cmp_lt_u32 vcc_lo, 0x1000
	s_cselect_b32 vcc_hi, 1, 0
	s_sub_i32 vcc_lo, s87, 0x4100
	s_cmp_ge_u32 s94, 65
	s_cselect_b32 s89, vcc_lo, s89
	s_cselect_b32 vcc_hi, 1, vcc_hi
	s_cmp_lg_u32 vcc_hi, 0
	s_cselect_b32 s89, s89, 0
	s_lshl_b32 s42, s89, 12
	s_lshl_b32 vcc_hi, vcc_hi, 1
	s_or_b32 s19, s19, vcc_hi
	s_add_u32 s22, s96, s42
	s_addc_u32 s23, s97, 0
	global_load_dwordx4 v[192:195], v151, s[22:23]
	global_load_dwordx4 v[196:199], v151, s[22:23] offset:16
	global_load_dwordx4 v[200:203], v151, s[22:23] offset:512
	global_load_dwordx4 v[204:207], v151, s[22:23] offset:528
	s_add_i32 s87, s21, 32
	s_mul_hi_u32 s89, s87, 0x7e07e07f
	s_lshr_b32 s89, s89, 11
	s_mul_i32 vcc_lo, s89, 0x1040
	s_sub_i32 vcc_lo, s87, vcc_lo
	s_add_i32 vcc_lo, vcc_lo, -16
	s_lshl_b32 s89, s89, 12
	s_add_i32 s89, s89, vcc_lo
	s_cmp_lt_u32 vcc_lo, 0x1000
	s_cselect_b32 vcc_hi, 1, 0
	s_sub_i32 vcc_lo, s87, 0x4100
	s_cmp_ge_u32 s94, 65
	s_cselect_b32 s89, vcc_lo, s89
	s_cselect_b32 vcc_hi, 1, vcc_hi
	s_cmp_lg_u32 vcc_hi, 0
	s_cselect_b32 s89, s89, 0
	s_lshl_b32 s43, s89, 12
	s_lshl_b32 vcc_hi, vcc_hi, 2
	s_or_b32 s19, s19, vcc_hi
	s_add_u32 s22, s96, s43
	s_addc_u32 s23, s97, 0
	global_load_dwordx4 v[208:211], v151, s[22:23]
	global_load_dwordx4 v[212:215], v151, s[22:23] offset:16
	global_load_dwordx4 v[216:219], v151, s[22:23] offset:512
	global_load_dwordx4 v[220:223], v151, s[22:23] offset:528
	s_add_i32 s87, s21, 48
	s_mul_hi_u32 s89, s87, 0x7e07e07f
	s_lshr_b32 s89, s89, 11
	s_mul_i32 vcc_lo, s89, 0x1040
	s_sub_i32 vcc_lo, s87, vcc_lo
	s_add_i32 vcc_lo, vcc_lo, -16
	s_lshl_b32 s89, s89, 12
	s_add_i32 s89, s89, vcc_lo
	s_cmp_lt_u32 vcc_lo, 0x1000
	s_cselect_b32 vcc_hi, 1, 0
	s_sub_i32 vcc_lo, s87, 0x4100
	s_cmp_ge_u32 s94, 65
	s_cselect_b32 s89, vcc_lo, s89
	s_cselect_b32 vcc_hi, 1, vcc_hi
	s_cmp_lg_u32 vcc_hi, 0
	s_cselect_b32 s89, s89, 0
	s_lshl_b32 s95, s89, 12
	s_lshl_b32 vcc_hi, vcc_hi, 3
	s_or_b32 s19, s19, vcc_hi
	s_add_u32 s22, s96, s95
	s_addc_u32 s23, s97, 0
	global_load_dwordx4 v[224:227], v151, s[22:23]
	global_load_dwordx4 v[228:231], v151, s[22:23] offset:16
	global_load_dwordx4 v[232:235], v151, s[22:23] offset:512
	global_load_dwordx4 v[236:239], v151, s[22:23] offset:528
	s_waitcnt vmcnt(0)
	v_pk_add_f32 v[124:125], v[124:125], v[176:177]
	v_pk_add_f32 v[126:127], v[126:127], v[178:179]
	v_pk_add_f32 v[120:121], v[120:121], v[180:181]
	v_pk_add_f32 v[122:123], v[122:123], v[182:183]
	v_pk_add_f32 v[116:117], v[116:117], v[184:185]
	v_pk_add_f32 v[118:119], v[118:119], v[186:187]
	v_pk_add_f32 v[112:113], v[112:113], v[188:189]
	v_pk_add_f32 v[114:115], v[114:115], v[190:191]
	v_pk_mul_f32 v[172:173], v[124:125], v[124:125]
	v_pk_fma_f32 v[172:173], v[126:127], v[126:127], v[172:173]
	v_pk_fma_f32 v[172:173], v[120:121], v[120:121], v[172:173]
	v_pk_fma_f32 v[172:173], v[122:123], v[122:123], v[172:173]
	v_pk_fma_f32 v[172:173], v[116:117], v[116:117], v[172:173]
	v_pk_fma_f32 v[172:173], v[118:119], v[118:119], v[172:173]
	v_pk_fma_f32 v[172:173], v[112:113], v[112:113], v[172:173]
	v_pk_fma_f32 v[172:173], v[114:115], v[114:115], v[172:173]
	s_nop 0
	v_add_f32_e32 v168, v172, v173
	s_add_i32 s87, s21, 128
	s_mul_hi_u32 s89, s87, 0x7e07e07f
	s_lshr_b32 s89, s89, 11
	s_mul_i32 vcc_lo, s89, 0x1040
	s_sub_i32 vcc_lo, s87, vcc_lo
	s_add_i32 vcc_lo, vcc_lo, -16
	s_lshl_b32 s89, s89, 12
	s_add_i32 s89, s89, vcc_lo
	s_cmp_lt_u32 vcc_lo, 0x1000
	s_cselect_b32 vcc_hi, 1, 0
	s_sub_i32 vcc_lo, s87, 0x4100
	s_cmp_ge_u32 s94, 65
	s_cselect_b32 s89, vcc_lo, s89
	s_cselect_b32 vcc_hi, 1, vcc_hi
	s_cmp_lg_u32 vcc_hi, 0
	s_cselect_b32 s89, s89, 0
	s_lshl_b32 s20, s89, 12
	s_lshl_b32 vcc_hi, vcc_hi, 4
	s_or_b32 s19, s19, vcc_hi
	s_add_u32 s22, s96, s20
	s_addc_u32 s23, s97, 0
	global_load_dwordx4 v[176:179], v151, s[22:23]
	global_load_dwordx4 v[180:183], v151, s[22:23] offset:16
	global_load_dwordx4 v[184:187], v151, s[22:23] offset:512
	global_load_dwordx4 v[188:191], v151, s[22:23] offset:528
;     DI void operator()(const f32x4 (&acc)[2][2][4][2], const pg8::Unit& u, int wr, int wc, int fr, int fq) const {
;     ...
;                 float ss = 0.f;
;                 if (xs) {
; #pragma unroll
;                     for (int bj = 0; bj < 2; ++bj) {
;                         const int n = colt + bj * 128 + wc * 32 + 8 * fq;
;                         const f32x4 x0 = *(const f32x4*)(xs + n), x1 = *(const f32x4*)(xs + n + 4);
;                         const f32x4 h0 = x0 + acc[ai][bj][m][0], h1 = x1 + acc[ai][bj][m][1];
;                         *(f32x4*)(yd + n) = h0; *(f32x4*)(yd + n + 4) = h1;
;                         ss += h0[0] * h0[0] + h0[1] * h0[1] + h0[2] * h0[2] + h0[3] * h0[3] + h1[0] * h1[0] + h1[1] * h1[1] + h1[2] * h1[2] + h1[3] * h1[3];
;                     }
;                 }
;                 ss += __shfl_xor(ss, 16); ss += __shfl_xor(ss, 32);
;                 if (xs && fq == 0) atomicAdd(p.rowss + R, ss);
	v_pk_add_f32 v[108:109], v[108:109], v[192:193]
	v_pk_add_f32 v[110:111], v[110:111], v[194:195]
	v_pk_add_f32 v[104:105], v[104:105], v[196:197]
	v_pk_add_f32 v[106:107], v[106:107], v[198:199]
	v_pk_add_f32 v[100:101], v[100:101], v[200:201]
	v_pk_add_f32 v[102:103], v[102:103], v[202:203]
	v_pk_add_f32 v[96:97], v[96:97], v[204:205]
	v_pk_add_f32 v[98:99], v[98:99], v[206:207]
	v_pk_mul_f32 v[172:173], v[108:109], v[108:109]
	v_pk_fma_f32 v[172:173], v[110:111], v[110:111], v[172:173]
	v_pk_fma_f32 v[172:173], v[104:105], v[104:105], v[172:173]
	v_pk_fma_f32 v[172:173], v[106:107], v[106:107], v[172:173]
	v_pk_fma_f32 v[172:173], v[100:101], v[100:101], v[172:173]
	v_pk_fma_f32 v[172:173], v[102:103], v[102:103], v[172:173]
	v_pk_fma_f32 v[172:173], v[96:97], v[96:97], v[172:173]
	v_pk_fma_f32 v[172:173], v[98:99], v[98:99], v[172:173]
	s_nop 0
	v_add_f32_e32 v169, v172, v173
	s_add_i32 s87, s21, 144
	s_mul_hi_u32 s89, s87, 0x7e07e07f
	s_lshr_b32 s89, s89, 11
	s_mul_i32 vcc_lo, s89, 0x1040
	s_sub_i32 vcc_lo, s87, vcc_lo
	s_add_i32 vcc_lo, vcc_lo, -16
	s_lshl_b32 s89, s89, 12
	s_add_i32 s89, s89, vcc_lo
	s_cmp_lt_u32 vcc_lo, 0x1000
	s_cselect_b32 vcc_hi, 1, 0
	s_sub_i32 vcc_lo, s87, 0x4100
	s_cmp_ge_u32 s94, 65
	s_cselect_b32 s89, vcc_lo, s89
	s_cselect_b32 vcc_hi, 1, vcc_hi
	s_cmp_lg_u32 vcc_hi, 0
	s_cselect_b32 s89, s89, 0
	s_lshl_b32 s42, s89, 12
	s_lshl_b32 vcc_hi, vcc_hi, 5
	s_or_b32 s19, s19, vcc_hi
	s_add_u32 s22, s96, s42
	s_addc_u32 s23, s97, 0
	global_load_dwordx4 v[192:195], v151, s[22:23]
	global_load_dwordx4 v[196:199], v151, s[22:23] offset:16
	global_load_dwordx4 v[200:203], v151, s[22:23] offset:512
	global_load_dwordx4 v[204:207], v151, s[22:23] offset:528
	v_pk_add_f32 v[92:93], v[92:93], v[208:209]
	v_pk_add_f32 v[94:95], v[94:95], v[210:211]
	v_pk_add_f32 v[88:89], v[88:89], v[212:213]
	v_pk_add_f32 v[90:91], v[90:91], v[214:215]
	v_pk_add_f32 v[84:85], v[84:85], v[216:217]
	v_pk_add_f32 v[86:87], v[86:87], v[218:219]
	v_pk_add_f32 v[80:81], v[80:81], v[220:221]
	v_pk_add_f32 v[82:83], v[82:83], v[222:223]
	v_pk_mul_f32 v[172:173], v[92:93], v[92:93]
	v_pk_fma_f32 v[172:173], v[94:95], v[94:95], v[172:173]
	v_pk_fma_f32 v[172:173], v[88:89], v[88:89], v[172:173]
	v_pk_fma_f32 v[172:173], v[90:91], v[90:91], v[172:173]
	v_pk_fma_f32 v[172:173], v[84:85], v[84:85], v[172:173]
	v_pk_fma_f32 v[172:173], v[86:87], v[86:87], v[172:173]
	v_pk_fma_f32 v[172:173], v[80:81], v[80:81], v[172:173]
	v_pk_fma_f32 v[172:173], v[82:83], v[82:83], v[172:173]
	s_nop 0
	v_add_f32_e32 v170, v172, v173
	s_add_i32 s87, s21, 160
	s_mul_hi_u32 s89, s87, 0x7e07e07f
	s_lshr_b32 s89, s89, 11
	s_mul_i32 vcc_lo, s89, 0x1040
	s_sub_i32 vcc_lo, s87, vcc_lo
	s_add_i32 vcc_lo, vcc_lo, -16
	s_lshl_b32 s89, s89, 12
	s_add_i32 s89, s89, vcc_lo
	s_cmp_lt_u32 vcc_lo, 0x1000
	s_cselect_b32 vcc_hi, 1, 0
	s_sub_i32 vcc_lo, s87, 0x4100
	s_cmp_ge_u32 s94, 65
	s_cselect_b32 s89, vcc_lo, s89
	s_cselect_b32 vcc_hi, 1, vcc_hi
	s_cmp_lg_u32 vcc_hi, 0
	s_cselect_b32 s89, s89, 0
	s_lshl_b32 s43, s89, 12
	s_lshl_b32 vcc_hi, vcc_hi, 6
	s_or_b32 s19, s19, vcc_hi
	s_add_u32 s22, s96, s43
	s_addc_u32 s23, s97, 0
	global_load_dwordx4 v[208:211], v151, s[22:23]
	global_load_dwordx4 v[212:215], v151, s[22:23] offset:16
	global_load_dwordx4 v[216:219], v151, s[22:23] offset:512
	global_load_dwordx4 v[220:223], v151, s[22:23] offset:528
	v_pk_add_f32 v[76:77], v[76:77], v[224:225]
	v_pk_add_f32 v[78:79], v[78:79], v[226:227]
	v_pk_add_f32 v[72:73], v[72:73], v[228:229]
	v_pk_add_f32 v[74:75], v[74:75], v[230:231]
	v_pk_add_f32 v[68:69], v[68:69], v[232:233]
	v_pk_add_f32 v[70:71], v[70:71], v[234:235]
	v_pk_add_f32 v[64:65], v[64:65], v[236:237]
	v_pk_add_f32 v[66:67], v[66:67], v[238:239]
	v_pk_mul_f32 v[172:173], v[76:77], v[76:77]
	v_pk_fma_f32 v[172:173], v[78:79], v[78:79], v[172:173]
	v_pk_fma_f32 v[172:173], v[72:73], v[72:73], v[172:173]
	v_pk_fma_f32 v[172:173], v[74:75], v[74:75], v[172:173]
	v_pk_fma_f32 v[172:173], v[68:69], v[68:69], v[172:173]
	v_pk_fma_f32 v[172:173], v[70:71], v[70:71], v[172:173]
	v_pk_fma_f32 v[172:173], v[64:65], v[64:65], v[172:173]
	v_pk_fma_f32 v[172:173], v[66:67], v[66:67], v[172:173]
	s_nop 0
	v_add_f32_e32 v171, v172, v173
	s_add_i32 s87, s21, 176
	s_mul_hi_u32 s89, s87, 0x7e07e07f
	s_lshr_b32 s89, s89, 11
	s_mul_i32 vcc_lo, s89, 0x1040
	s_sub_i32 vcc_lo, s87, vcc_lo
	s_add_i32 vcc_lo, vcc_lo, -16
	s_lshl_b32 s89, s89, 12
	s_add_i32 s89, s89, vcc_lo
	s_cmp_lt_u32 vcc_lo, 0x1000
	s_cselect_b32 vcc_hi, 1, 0
	s_sub_i32 vcc_lo, s87, 0x4100
	s_cmp_ge_u32 s94, 65
	s_cselect_b32 s89, vcc_lo, s89
	s_cselect_b32 vcc_hi, 1, vcc_hi
	s_cmp_lg_u32 vcc_hi, 0
	s_cselect_b32 s89, s89, 0
	s_lshl_b32 s95, s89, 12
	s_lshl_b32 vcc_hi, vcc_hi, 7
	s_or_b32 s19, s19, vcc_hi
	s_add_u32 s22, s96, s95
	s_addc_u32 s23, s97, 0
	global_load_dwordx4 v[224:227], v151, s[22:23]
	global_load_dwordx4 v[228:231], v151, s[22:23] offset:16
	global_load_dwordx4 v[232:235], v151, s[22:23] offset:512
	global_load_dwordx4 v[236:239], v151, s[22:23] offset:528
	ds_bpermute_b32 v155, v153, v168
	ds_bpermute_b32 v156, v153, v169
	ds_bpermute_b32 v157, v153, v170
	ds_bpermute_b32 v132, v153, v171
	s_waitcnt lgkmcnt(0)
	v_add_f32_e32 v168, v168, v155
	v_add_f32_e32 v169, v169, v156
	v_add_f32_e32 v170, v170, v157
	v_add_f32_e32 v171, v171, v132
	ds_bpermute_b32 v155, v154, v168
	ds_bpermute_b32 v156, v154, v169
	ds_bpermute_b32 v157, v154, v170
	ds_bpermute_b32 v132, v154, v171
	s_waitcnt lgkmcnt(0)
	v_add_f32_e32 v168, v168, v155
	v_add_f32_e32 v169, v169, v156
	v_add_f32_e32 v170, v170, v157
	v_add_f32_e32 v171, v171, v132
	s_mov_b64 exec, s[36:37]
	s_bitcmp1_b32 s19, 0
	s_cbranch_scc0 .Lf3f_at_b0_0
	global_atomic_add_f32 v152, v168, s[60:61]

;     DI void operator()(const f32x4 (&acc)[2][2][4][2], const pg8::Unit& u, int wr, int wc, int fr, int fq) const {
;     ...
;                 float ss = 0.f;
;                 if (xs) {
; #pragma unroll
;                     for (int bj = 0; bj < 2; ++bj) {
;                         const int n = colt + bj * 128 + wc * 32 + 8 * fq;
;                         const f32x4 x0 = *(const f32x4*)(xs + n), x1 = *(const f32x4*)(xs + n + 4);
;                         const f32x4 h0 = x0 + acc[ai][bj][m][0], h1 = x1 + acc[ai][bj][m][1];
;                         *(f32x4*)(yd + n) = h0; *(f32x4*)(yd + n + 4) = h1;
;                         ss += h0[0] * h0[0] + h0[1] * h0[1] + h0[2] * h0[2] + h0[3] * h0[3] + h1[0] * h1[0] + h1[1] * h1[1] + h1[2] * h1[2] + h1[3] * h1[3];
;                     }
;                 }
;                 ss += __shfl_xor(ss, 16); ss += __shfl_xor(ss, 32);
;                 if (xs && fq == 0) atomicAdd(p.rowss + R, ss);
.Lf3f_at_b0_3:
	s_mov_b64 exec, -1
	s_waitcnt vmcnt(0)
	v_pk_add_f32 v[60:61], v[60:61], v[176:177]
	v_pk_add_f32 v[62:63], v[62:63], v[178:179]
	v_pk_add_f32 v[56:57], v[56:57], v[180:181]
	v_pk_add_f32 v[58:59], v[58:59], v[182:183]
	v_pk_add_f32 v[52:53], v[52:53], v[184:185]
	v_pk_add_f32 v[54:55], v[54:55], v[186:187]
	v_pk_add_f32 v[48:49], v[48:49], v[188:189]
	v_pk_add_f32 v[50:51], v[50:51], v[190:191]
	v_pk_mul_f32 v[172:173], v[60:61], v[60:61]
	v_pk_fma_f32 v[172:173], v[62:63], v[62:63], v[172:173]
	v_pk_fma_f32 v[172:173], v[56:57], v[56:57], v[172:173]
	v_pk_fma_f32 v[172:173], v[58:59], v[58:59], v[172:173]
	v_pk_fma_f32 v[172:173], v[52:53], v[52:53], v[172:173]
	v_pk_fma_f32 v[172:173], v[54:55], v[54:55], v[172:173]
	v_pk_fma_f32 v[172:173], v[48:49], v[48:49], v[172:173]
	v_pk_fma_f32 v[172:173], v[50:51], v[50:51], v[172:173]
	s_nop 0
	v_add_f32_e32 v168, v172, v173
	v_pk_add_f32 v[44:45], v[44:45], v[192:193]
	v_pk_add_f32 v[46:47], v[46:47], v[194:195]
	v_pk_add_f32 v[40:41], v[40:41], v[196:197]
	v_pk_add_f32 v[42:43], v[42:43], v[198:199]
	v_pk_add_f32 v[36:37], v[36:37], v[200:201]
	v_pk_add_f32 v[38:39], v[38:39], v[202:203]
	v_pk_add_f32 v[32:33], v[32:33], v[204:205]
	v_pk_add_f32 v[34:35], v[34:35], v[206:207]
	v_pk_mul_f32 v[172:173], v[44:45], v[44:45]
	v_pk_fma_f32 v[172:173], v[46:47], v[46:47], v[172:173]
	v_pk_fma_f32 v[172:173], v[40:41], v[40:41], v[172:173]
	v_pk_fma_f32 v[172:173], v[42:43], v[42:43], v[172:173]
	v_pk_fma_f32 v[172:173], v[36:37], v[36:37], v[172:173]
	v_pk_fma_f32 v[172:173], v[38:39], v[38:39], v[172:173]
	v_pk_fma_f32 v[172:173], v[32:33], v[32:33], v[172:173]
	v_pk_fma_f32 v[172:173], v[34:35], v[34:35], v[172:173]
	s_nop 0
	v_add_f32_e32 v169, v172, v173
	v_pk_add_f32 v[28:29], v[28:29], v[208:209]
	v_pk_add_f32 v[30:31], v[30:31], v[210:211]
	v_pk_add_f32 v[24:25], v[24:25], v[212:213]
	v_pk_add_f32 v[26:27], v[26:27], v[214:215]
	v_pk_add_f32 v[20:21], v[20:21], v[216:217]
	v_pk_add_f32 v[22:23], v[22:23], v[218:219]
	v_pk_add_f32 v[16:17], v[16:17], v[220:221]
	v_pk_add_f32 v[18:19], v[18:19], v[222:223]
	v_pk_mul_f32 v[172:173], v[28:29], v[28:29]
	v_pk_fma_f32 v[172:173], v[30:31], v[30:31], v[172:173]
	v_pk_fma_f32 v[172:173], v[24:25], v[24:25], v[172:173]
	v_pk_fma_f32 v[172:173], v[26:27], v[26:27], v[172:173]
	v_pk_fma_f32 v[172:173], v[20:21], v[20:21], v[172:173]
	v_pk_fma_f32 v[172:173], v[22:23], v[22:23], v[172:173]
	v_pk_fma_f32 v[172:173], v[16:17], v[16:17], v[172:173]
	v_pk_fma_f32 v[172:173], v[18:19], v[18:19], v[172:173]
	s_nop 0
	v_add_f32_e32 v170, v172, v173
	v_pk_add_f32 v[12:13], v[12:13], v[224:225]
	v_pk_add_f32 v[14:15], v[14:15], v[226:227]
	v_pk_add_f32 v[8:9], v[8:9], v[228:229]
	v_pk_add_f32 v[10:11], v[10:11], v[230:231]
	v_pk_add_f32 v[4:5], v[4:5], v[232:233]
	v_pk_add_f32 v[6:7], v[6:7], v[234:235]
	v_pk_add_f32 v[0:1], v[0:1], v[236:237]
	v_pk_add_f32 v[2:3], v[2:3], v[238:239]
	v_pk_mul_f32 v[172:173], v[12:13], v[12:13]
	v_pk_fma_f32 v[172:173], v[14:15], v[14:15], v[172:173]
	v_pk_fma_f32 v[172:173], v[8:9], v[8:9], v[172:173]
	v_pk_fma_f32 v[172:173], v[10:11], v[10:11], v[172:173]
	v_pk_fma_f32 v[172:173], v[4:5], v[4:5], v[172:173]
	v_pk_fma_f32 v[172:173], v[6:7], v[6:7], v[172:173]
	v_pk_fma_f32 v[172:173], v[0:1], v[0:1], v[172:173]
	v_pk_fma_f32 v[172:173], v[2:3], v[2:3], v[172:173]
	s_nop 0
	v_add_f32_e32 v171, v172, v173
	ds_bpermute_b32 v155, v153, v168
	ds_bpermute_b32 v156, v153, v169
	ds_bpermute_b32 v157, v153, v170
	ds_bpermute_b32 v132, v153, v171
	s_waitcnt lgkmcnt(0)
	v_add_f32_e32 v168, v168, v155
	v_add_f32_e32 v169, v169, v156
	v_add_f32_e32 v170, v170, v157
	v_add_f32_e32 v171, v171, v132
	ds_bpermute_b32 v155, v154, v168
	ds_bpermute_b32 v156, v154, v169
	ds_bpermute_b32 v157, v154, v170
	ds_bpermute_b32 v132, v154, v171
	s_waitcnt lgkmcnt(0)
	v_add_f32_e32 v168, v168, v155
	v_add_f32_e32 v169, v169, v156
	v_add_f32_e32 v170, v170, v157
	v_add_f32_e32 v171, v171, v132
	s_mov_b64 exec, s[36:37]
	s_bitcmp1_b32 s19, 4
	s_cbranch_scc0 .Lf3f_at_b1_0
	global_atomic_add_f32 v152, v168, s[60:61] offset:512

;     DI void operator()(const f32x4 (&acc)[2][2][4][2], const pg8::Unit& u, int wr, int wc, int fr, int fq) const {
;     ...
;                 ss += __shfl_xor(ss, 16); ss += __shfl_xor(ss, 32);
;                 if (xs && fq == 0) atomicAdd(p.rowss + R, ss);
; __global__ void __launch_bounds__(512, 2) hymba_mega(Params p) {
;     ...
;         f32x4 gq[4];
; #pragma unroll
;         for (int i = 0; i < 4; ++i) gq[i] = *(const f32x4*)(p.final_g + i * 256 + lane * 4);
.Lf3f_at_b1_3:
	s_mov_b64 exec, -1
	v_mov_b32_e32 v209, 0
	v_mov_b32_e32 v210, 1
	s_lshl_b32 s22, s94, 2
	s_add_i32 s22, s22, 96
	v_mov_b32_e32 v211, s22
	s_waitcnt vmcnt(0)
	s_barrier
	global_load_dwordx4 v[176:179], v150, s[52:53]
	global_load_dwordx4 v[180:183], v150, s[52:53] offset:16
	global_load_dwordx4 v[184:187], v150, s[52:53] offset:512
	global_load_dwordx4 v[188:191], v150, s[52:53] offset:528
	v_and_b32_e32 v208, 15, v174
	v_lshlrev_b32_e32 v208, 2, v208
	v_mov_b32_e32 v218, 0x358637bd
	v_mov_b32_e32 v219, 0x260
	s_movk_i32 s23, 4
	s_and_saveexec_b64 vcc, s[40:41]
	s_cbranch_execz .Lf3f_go_f
	global_atomic_add v212, v211, v210, s[56:57] sc0
	s_waitcnt vmcnt(0)
	v_readfirstlane_b32 s22, v212
	s_add_i32 s22, s22, 1
	s_cmp_ge_u32 s22, s23
	s_cbranch_scc1 .Lf3f_go_f
.Lf3f_poll_f:
	s_sleep 4
	global_atomic_add v212, v211, v209, s[56:57] sc0
	s_waitcnt vmcnt(0)
	v_readfirstlane_b32 s22, v212
	s_cmp_ge_u32 s22, s23
	s_cbranch_scc0 .Lf3f_poll_f

;     DI void operator()(const f32x4 (&acc)[2][2][4][2], const pg8::Unit& u, int wr, int wc, int fr, int fq) const {
;     ...
;                 ss += __shfl_xor(ss, 16); ss += __shfl_xor(ss, 32);
;                 if (xs && fq == 0) atomicAdd(p.rowss + R, ss);
; __global__ void __launch_bounds__(512, 2) hymba_mega(Params p) {
;     ...
;         f32x4 gq[4];
; #pragma unroll
;         for (int i = 0; i < 4; ++i) gq[i] = *(const f32x4*)(p.final_g + i * 256 + lane * 4);
.Lf3q0_at_q_3:
	s_mov_b64 exec, -1
	v_mov_b32_e32 v209, 0
	v_mov_b32_e32 v210, 1
	s_lshl_b32 s22, s94, 2
	s_add_i32 s22, s22, 96
	v_mov_b32_e32 v211, s22
	s_waitcnt vmcnt(0)
	s_barrier
	global_load_dwordx4 v[176:179], v150, s[52:53]
	global_load_dwordx4 v[180:183], v150, s[52:53] offset:16
	global_load_dwordx4 v[184:187], v150, s[52:53] offset:512
	global_load_dwordx4 v[188:191], v150, s[52:53] offset:528
	v_and_b32_e32 v208, 15, v174
	v_lshlrev_b32_e32 v208, 2, v208
	v_mov_b32_e32 v218, 0x358637bd
	v_mov_b32_e32 v219, 0x260
	s_movk_i32 s23, 16
	s_and_saveexec_b64 vcc, s[40:41]
	s_cbranch_execz .Lf3q0_go_q
	global_atomic_add v212, v211, v210, s[56:57] sc0
	s_waitcnt vmcnt(0)
	v_readfirstlane_b32 s22, v212
	s_add_i32 s22, s22, 1
	s_cmp_ge_u32 s22, s23
	s_cbranch_scc1 .Lf3q0_go_q
